# attention loops: LDS buffer bases carried in SGPRs instead of recomputed mod 3 per tile
# baseline (speedup 1.0000x reference)
; #define LAS __attribute__((address_space(3)))
; __device__ __forceinline__ void attn_unit(LAS unsigned char* lds, const bf16_t* Q, const bf16_t* KV, const bf16_t* KR, bf16_t* MIX, size_t qrow0, size_t krow0, int ntiles, int h, const int tid) {
;     ...
;   float mref[2] = {0.f, 0.f}; f32x4 lacc[2] = {(f32x4){0.f, 0.f, 0.f, 0.f}, (f32x4){0.f, 0.f, 0.f, 0.f}};
;   const bf16x8 ones = (bf16x8){0x3F80, 0x3F80, 0x3F80, 0x3F80, 0x3F80, 0x3F80, 0x3F80, 0x3F80};
;   u32x4 rk = *(const u32x4*)gk, rv = *(const u32x4*)(gk + 64), rr = (u32x4){0, 0, 0, 0};
;   if (tid < 256) rr = *(const u32x4*)gr;
;   __syncthreads();
;   attn_stage(lds, tid, rk, rv, rr);
;   __syncthreads();
;   for (int t = 0; t < ntiles; ++t) {
;     LAS unsigned char* buf = lds + (t & 1) * AT_BUF;
;     const bool more = (t + 1 < ntiles);
;     if (more) { const bf16_t* g2 = gk + (size_t)(t + 1) * 64 * 1024; rk = *(const u32x4*)g2; rv = *(const u32x4*)(g2 + 64); if (tid < 256) rr = *(const u32x4*)(gr + (size_t)(t + 1) * 64 * 32); }
.LBB0_382:
	s_or_b64 exec, exec, s[4:5]
	s_and_b32 s4, s8, 7
	s_mul_i32 s5, s4, 0x84000
	s_mul_i32 s4, s4, 0x1080000
	s_lshl_b64 s[0:1], s[0:1], 1
	s_add_u32 s0, s4, s0
	v_or_b32_e32 v0, s5, v121
	s_addc_u32 s1, 0, s1
	v_pk_add_f32 v[2:3], v[2:3], 0 op_sel_hi:[1,0]
	v_lshl_add_u64 v[140:141], v[132:133], 0, v[0:1]
	v_lshl_add_u64 v[142:143], v[134:135], 0, s[0:1]
	s_mov_b32 s4, 2
	s_waitcnt vmcnt(0)
	ds_write_b128 v151, v[72:75] offset:35840
	s_waitcnt lgkmcnt(0)
	s_barrier
	v_mov_b32_e32 v198, 0x3f803f80
	v_mov_b32_e32 v199, v198
	v_mov_b32_e32 v200, v198
	v_mov_b32_e32 v201, v198
	v_xor_b32_e32 v202, 0x80000000, v2
	v_xor_b32_e32 v206, 0x80000000, v3
	v_lshlrev_b32_e32 v176, 1, v154
	v_mov_b32_e32 v203, v202
	v_mov_b32_e32 v204, v202
	v_mov_b32_e32 v205, v202
	v_mov_b32_e32 v207, v206
	v_mov_b32_e32 v208, v206
	v_mov_b32_e32 v209, v206
	s_movk_i32 s12, 0x5800
	s_mov_b32 s13, 0xb000
	s_mov_b32 s14, 0
	s_cmp_lg_u32 s42, 0
	s_cbranch_scc1 .LBB0_384
	global_load_dwordx4 v[76:79], v[142:143], off
	global_load_dwordx4 v[72:75], v[142:143], off offset:128
	v_add3_u32 v0, s12, v124, v146
	ds_read_b128 v[170:173], v0
	ds_read_b128 v[210:213], v0 offset:64
	ds_read_b128 v[214:217], v0 offset:128
	ds_read_b128 v[218:221], v0 offset:3328
	ds_read_b128 v[166:169], v0 offset:3392
	s_branch .Lat_B_mid

; #define LAS __attribute__((address_space(3)))
; __device__ __forceinline__ f32x4 mfma16(bf16x8 a, bf16x8 b, f32x4 c) { return __builtin_amdgcn_mfma_f32_16x16x32_bf16(a, b, c, 0, 0, 0); }
; __device__ __forceinline__ void attn_unit(LAS unsigned char* lds, const bf16_t* Q, const bf16_t* KV, const bf16_t* KR, bf16_t* MIX, size_t qrow0, size_t krow0, int ntiles, int h, const int tid) {
;     ...
; #pragma unroll
;     for (int kb = 0; kb < 4; ++kb) {
;       bf16x8 kf[3];
; #pragma unroll
;       for (int ks = 0; ks < 3; ++ks) kf[ks] = *(const LAS bf16x8*)(Ks + (kb * 16 + c16) * AT_KSTR + ks * 32 + quad * 8);
; #pragma unroll
;       for (int qb = 0; qb < 2; ++qb) { const float nm = -mref[qb]; f32x4 a = (f32x4){nm, nm, nm, nm};
; #pragma unroll
;         for (int ks = 0; ks < 3; ++ks) a = mfma16(kf[ks], qf[qb][ks], a);
;         s[kb][qb] = a; }
;     }
; #pragma unroll
;     for (int qb = 0; qb < 2; ++qb) {
;       float mx = -1e30f;
; #pragma unroll
;       for (int kb = 0; kb < 4; ++kb) mx = fmaxf(fmaxf(fmaxf(s[kb][qb][0], s[kb][qb][1]), fmaxf(s[kb][qb][2], s[kb][qb][3])), mx);
;       mx = fmaxf(mx, __shfl_xor(mx, 16)); mx = fmaxf(mx, __shfl_xor(mx, 32));
;       if (t == 0 || __any(mx > 8.f)) {
.Lat_B_top:
	global_load_dwordx4 v[76:79], v[142:143], off
	global_load_dwordx4 v[72:75], v[142:143], off offset:128
	v_add3_u32 v139, s14, v176, v155
	ds_read_b64_tr_b16 v[170:171], v139 offset:13312
	ds_read_b64_tr_b16 v[172:173], v139 offset:15616
	ds_read_b64_tr_b16 v[210:211], v139 offset:13344
	ds_read_b64_tr_b16 v[212:213], v139 offset:15648
	ds_read_b64_tr_b16 v[214:215], v139 offset:13376
	ds_read_b64_tr_b16 v[216:217], v139 offset:15680
	ds_read_b64_tr_b16 v[218:219], v139 offset:13408
	ds_read_b64_tr_b16 v[220:221], v139 offset:15712
	ds_read_b64_tr_b16 v[240:241], v139 offset:17920
	ds_read_b64_tr_b16 v[242:243], v139 offset:20224
	ds_read_b64_tr_b16 v[244:245], v139 offset:17952
	ds_read_b64_tr_b16 v[246:247], v139 offset:20256
	ds_read_b64_tr_b16 v[158:159], v139 offset:17984
	ds_read_b64_tr_b16 v[160:161], v139 offset:20288
	s_waitcnt lgkmcnt(12)
	v_mfma_f32_16x16x32_bf16 v[52:55], v[170:173], v[80:83], v[52:55]
	v_mfma_f32_16x16x32_bf16 v[48:51], v[170:173], v[88:91], v[48:51]
	ds_read_b64_tr_b16 v[162:163], v139 offset:18016
	ds_read_b64_tr_b16 v[164:165], v139 offset:20320
	v_mfma_f32_16x16x32_bf16 v[60:63], v[198:201], v[80:83], v[60:63]
	v_mfma_f32_16x16x32_bf16 v[56:59], v[198:201], v[88:91], v[56:59]
	s_waitcnt lgkmcnt(12)
	v_mfma_f32_16x16x32_bf16 v[68:71], v[210:213], v[80:83], v[68:71]
	v_mfma_f32_16x16x32_bf16 v[64:67], v[210:213], v[88:91], v[64:67]
	s_waitcnt lgkmcnt(10)
	v_mfma_f32_16x16x32_bf16 v[44:47], v[214:217], v[80:83], v[44:47]
	v_mfma_f32_16x16x32_bf16 v[40:43], v[214:217], v[88:91], v[40:43]
	s_waitcnt lgkmcnt(8)
	v_mfma_f32_16x16x32_bf16 v[36:39], v[218:221], v[80:83], v[36:39]
	v_mfma_f32_16x16x32_bf16 v[32:35], v[218:221], v[88:91], v[32:35]
	v_add3_u32 v0, s12, v124, v146
	ds_read_b128 v[170:173], v0
	ds_read_b128 v[210:213], v0 offset:64
	ds_read_b128 v[214:217], v0 offset:128
	ds_read_b128 v[218:221], v0 offset:3328
	ds_read_b128 v[166:169], v0 offset:3392
	v_mfma_f32_16x16x32_bf16 v[60:63], v[198:201], v[96:99], v[60:63]
	v_mfma_f32_16x16x32_bf16 v[56:59], v[198:201], v[104:107], v[56:59]
	s_waitcnt lgkmcnt(11)
	v_mfma_f32_16x16x32_bf16 v[52:55], v[240:243], v[96:99], v[52:55]
	v_mfma_f32_16x16x32_bf16 v[48:51], v[240:243], v[104:107], v[48:51]
	s_waitcnt lgkmcnt(9)
	v_mfma_f32_16x16x32_bf16 v[68:71], v[244:247], v[96:99], v[68:71]
	v_mfma_f32_16x16x32_bf16 v[64:67], v[244:247], v[104:107], v[64:67]
	s_waitcnt lgkmcnt(7)
	v_mfma_f32_16x16x32_bf16 v[44:47], v[158:161], v[96:99], v[44:47]
	v_mfma_f32_16x16x32_bf16 v[40:43], v[158:161], v[104:107], v[40:43]
	s_waitcnt lgkmcnt(5)
	v_mfma_f32_16x16x32_bf16 v[36:39], v[162:165], v[96:99], v[36:39]
	v_mfma_f32_16x16x32_bf16 v[32:35], v[162:165], v[104:107], v[32:35]
.Lat_B_mid:
	ds_read_b128 v[240:243], v0 offset:3456
	ds_read_b128 v[244:247], v0 offset:6656
	ds_read_b128 v[158:161], v0 offset:6720
	ds_read_b128 v[162:165], v0 offset:6784
	s_waitcnt lgkmcnt(8)
	v_mfma_f32_16x16x32_bf16 v[80:83], v[170:173], v[4:7], v[202:205]
	v_mfma_f32_16x16x32_bf16 v[88:91], v[170:173], v[16:19], v[206:209]
	s_waitcnt lgkmcnt(7)
	v_mfma_f32_16x16x32_bf16 v[80:83], v[210:213], v[8:11], v[80:83]
	v_mfma_f32_16x16x32_bf16 v[88:91], v[210:213], v[20:23], v[88:91]
	s_waitcnt lgkmcnt(6)
	v_mfma_f32_16x16x32_bf16 v[80:83], v[214:217], v[12:15], v[80:83]
	v_mfma_f32_16x16x32_bf16 v[88:91], v[214:217], v[24:27], v[88:91]
	ds_read_b128 v[170:173], v0 offset:9984
	ds_read_b128 v[210:213], v0 offset:10048
	ds_read_b128 v[214:217], v0 offset:10112
	s_waitcnt lgkmcnt(8)
	v_mfma_f32_16x16x32_bf16 v[84:87], v[218:221], v[4:7], v[202:205]
	v_mfma_f32_16x16x32_bf16 v[92:95], v[218:221], v[16:19], v[206:209]
	s_waitcnt lgkmcnt(7)
	v_mfma_f32_16x16x32_bf16 v[84:87], v[166:169], v[8:11], v[84:87]
	v_mfma_f32_16x16x32_bf16 v[92:95], v[166:169], v[20:23], v[92:95]
	s_waitcnt lgkmcnt(6)
	v_mfma_f32_16x16x32_bf16 v[84:87], v[240:243], v[12:15], v[84:87]
	v_mfma_f32_16x16x32_bf16 v[92:95], v[240:243], v[24:27], v[92:95]
	s_waitcnt lgkmcnt(5)
	v_mfma_f32_16x16x32_bf16 v[96:99], v[244:247], v[4:7], v[202:205]
	v_mfma_f32_16x16x32_bf16 v[104:107], v[244:247], v[16:19], v[206:209]
	v_max3_f32 v174, v80, v81, v82
	s_waitcnt lgkmcnt(4)
	v_mfma_f32_16x16x32_bf16 v[96:99], v[158:161], v[8:11], v[96:99]
	v_mfma_f32_16x16x32_bf16 v[104:107], v[158:161], v[20:23], v[104:107]
	v_max3_f32 v175, v88, v89, v90
	s_waitcnt lgkmcnt(3)
	v_mfma_f32_16x16x32_bf16 v[96:99], v[162:165], v[12:15], v[96:99]
	v_mfma_f32_16x16x32_bf16 v[104:107], v[162:165], v[24:27], v[104:107]
	s_waitcnt lgkmcnt(2)
	v_mfma_f32_16x16x32_bf16 v[100:103], v[170:173], v[4:7], v[202:205]
	v_mfma_f32_16x16x32_bf16 v[108:111], v[170:173], v[16:19], v[206:209]
	v_max3_f32 v174, v174, v83, v84
	s_waitcnt lgkmcnt(1)
	v_mfma_f32_16x16x32_bf16 v[100:103], v[210:213], v[8:11], v[100:103]
	v_max3_f32 v174, v174, v85, v86
	v_mfma_f32_16x16x32_bf16 v[108:111], v[210:213], v[20:23], v[108:111]
	s_waitcnt lgkmcnt(0)
	v_mfma_f32_16x16x32_bf16 v[100:103], v[214:217], v[12:15], v[100:103]
	v_max3_f32 v175, v175, v91, v92
	v_mfma_f32_16x16x32_bf16 v[108:111], v[214:217], v[24:27], v[108:111]
	v_max3_f32 v175, v175, v93, v94
	v_max3_f32 v174, v174, v87, v96
	v_max3_f32 v174, v174, v97, v98
	v_max3_f32 v175, v175, v95, v104
	v_max3_f32 v175, v175, v105, v106
	v_add3_u32 v0, s13, v148, v138
	v_add3_u32 v177, s13, v127, v138
	s_nop 0
	v_max3_f32 v174, v174, v99, v100
	v_max3_f32 v175, v175, v107, v108
	v_max3_f32 v174, v174, v101, v102
	v_max3_f32 v175, v175, v109, v110
	v_max_f32_e32 v174, v174, v103
	v_max_f32_e32 v175, v175, v111
	v_max_f32_e32 v235, v174, v175
	v_cmp_lt_f32_e32 vcc, 0x41000000, v235
	s_cbranch_vccnz .Lat_rareB
; #define LAS __attribute__((address_space(3)))
; __device__ __forceinline__ unsigned cvtpk(float lo, float hi) { f32x2_t v = {lo, hi}; bf16x2_t b = __builtin_convertvector(v, bf16x2_t); return __builtin_bit_cast(unsigned, b); }
; __device__ __forceinline__ f32x4 mfma16(bf16x8 a, bf16x8 b, f32x4 c) { return __builtin_amdgcn_mfma_f32_16x16x32_bf16(a, b, c, 0, 0, 0); }
; __device__ __forceinline__ u32x2 tr_rd(const LAS bf16_t* p) { return __builtin_bit_cast(u32x2, __builtin_amdgcn_ds_read_tr16_b64_v4i16((LAS v4i16_t*)p)); }
; __device__ __forceinline__ void attn_unit(LAS unsigned char* lds, const bf16_t* Q, const bf16_t* KV, const bf16_t* KR, bf16_t* MIX, size_t qrow0, size_t krow0, int ntiles, int h, const int tid) {
;     ...
;         for (int r = 0; r < 4; ++r) s[kb][qb][r] = __builtin_amdgcn_exp2f(s[kb][qb][r]);
;     }
; #pragma unroll
;     for (int s2 = 0; s2 < 2; ++s2) {
;       bf16x8 pf[2];
; #pragma unroll
;       for (int qb = 0; qb < 2; ++qb) { u32x4 w; w.x = cvtpk(s[2 * s2][qb][0], s[2 * s2][qb][1]); w.y = cvtpk(s[2 * s2][qb][2], s[2 * s2][qb][3]);
;         w.z = cvtpk(s[2 * s2 + 1][qb][0], s[2 * s2 + 1][qb][1]); w.w = cvtpk(s[2 * s2 + 1][qb][2], s[2 * s2 + 1][qb][3]); pf[qb] = __builtin_bit_cast(bf16x8, w);
;         lacc[qb] = mfma16(ones, pf[qb], lacc[qb]); }
;       const LAS bf16_t* vb = Vs + (32 * s2 + 4 * quad + tq) * AT_VSTR + 4 * tp;
; #pragma unroll
;       for (int eb = 0; eb < 4; ++eb) {
;         const u32x2 lo = tr_rd(vb + 16 * eb), hi = tr_rd(vb + 16 * AT_VSTR + 16 * eb);
;         const u32x4 vv = (u32x4){lo.x, lo.y, hi.x, hi.y}; const bf16x8 vf = __builtin_bit_cast(bf16x8, vv);
; #pragma unroll
;         for (int qb = 0; qb < 2; ++qb) o[qb][eb] = mfma16(vf, pf[qb], o[qb][eb]);
;       }
;     }
;     if (more) attn_stage(lds + ((t + 1) & 1) * AT_BUF, tid, rk, rv, rr);
;     __syncthreads();
.Lat_backB:
	v_exp_f32_e32 v80, v80
	v_exp_f32_e32 v81, v81
	v_exp_f32_e32 v82, v82
	v_exp_f32_e32 v83, v83
	v_exp_f32_e32 v84, v84
	v_exp_f32_e32 v85, v85
	v_exp_f32_e32 v86, v86
	v_exp_f32_e32 v87, v87
	v_cvt_pk_bf16_f32 v80, v80, v81
	v_cvt_pk_bf16_f32 v81, v82, v83
	v_cvt_pk_bf16_f32 v82, v84, v85
	v_cvt_pk_bf16_f32 v83, v86, v87
	v_exp_f32_e32 v88, v88
	v_exp_f32_e32 v89, v89
	v_exp_f32_e32 v90, v90
	v_exp_f32_e32 v91, v91
	v_exp_f32_e32 v92, v92
	v_exp_f32_e32 v93, v93
	v_exp_f32_e32 v94, v94
	v_exp_f32_e32 v95, v95
	v_cvt_pk_bf16_f32 v88, v88, v89
	v_cvt_pk_bf16_f32 v89, v90, v91
	v_cvt_pk_bf16_f32 v90, v92, v93
	v_cvt_pk_bf16_f32 v91, v94, v95
	v_exp_f32_e32 v96, v96
	v_exp_f32_e32 v97, v97
	v_exp_f32_e32 v98, v98
	v_exp_f32_e32 v99, v99
	v_exp_f32_e32 v100, v100
	v_exp_f32_e32 v101, v101
	v_exp_f32_e32 v102, v102
	v_exp_f32_e32 v103, v103
	v_cvt_pk_bf16_f32 v96, v96, v97
	v_cvt_pk_bf16_f32 v97, v98, v99
	v_cvt_pk_bf16_f32 v98, v100, v101
	v_cvt_pk_bf16_f32 v99, v102, v103
	v_exp_f32_e32 v104, v104
	v_exp_f32_e32 v105, v105
	v_exp_f32_e32 v106, v106
	v_exp_f32_e32 v107, v107
	v_exp_f32_e32 v108, v108
	v_exp_f32_e32 v109, v109
	v_exp_f32_e32 v110, v110
	v_exp_f32_e32 v111, v111
	v_cvt_pk_bf16_f32 v104, v104, v105
	v_cvt_pk_bf16_f32 v105, v106, v107
	v_cvt_pk_bf16_f32 v106, v108, v109
	v_cvt_pk_bf16_f32 v107, v110, v111
	s_waitcnt vmcnt(0)
	ds_write_b128 v0, v[76:79]
	ds_write_b128 v177, v[72:75] offset:13312
	s_mov_b64 s[0:1], 0x1000
	s_add_i32 s4, s4, 1
	v_lshl_add_u64 v[140:141], v[140:141], 0, s[0:1]
	s_mov_b64 s[0:1], 0x20000
	v_lshl_add_u64 v[142:143], v[142:143], 0, s[0:1]
	s_mov_b32 s14, s12
	s_mov_b32 s12, s13
	s_add_i32 s13, s13, 0x5800
	s_cmp_eq_u32 s13, 0x10800
	s_cselect_b32 s13, 0, s13
	s_cmpk_lg_i32 s4, 0x84
	s_waitcnt lgkmcnt(0)
	s_cbranch_scc1 .Lat_B_head
	s_barrier
	s_movk_i32 s0, 0x5800
	v_add3_u32 v139, s0, v176, v155
	ds_read_b64_tr_b16 v[170:171], v139 offset:13312
	ds_read_b64_tr_b16 v[172:173], v139 offset:15616
	ds_read_b64_tr_b16 v[210:211], v139 offset:13344
	ds_read_b64_tr_b16 v[212:213], v139 offset:15648
	ds_read_b64_tr_b16 v[214:215], v139 offset:13376
	ds_read_b64_tr_b16 v[216:217], v139 offset:15680
	ds_read_b64_tr_b16 v[218:219], v139 offset:13408
	ds_read_b64_tr_b16 v[220:221], v139 offset:15712
	ds_read_b64_tr_b16 v[240:241], v139 offset:17920
	ds_read_b64_tr_b16 v[242:243], v139 offset:20224
	ds_read_b64_tr_b16 v[244:245], v139 offset:17952
	ds_read_b64_tr_b16 v[246:247], v139 offset:20256
	ds_read_b64_tr_b16 v[158:159], v139 offset:17984
	ds_read_b64_tr_b16 v[160:161], v139 offset:20288
	s_waitcnt lgkmcnt(12)
	v_mfma_f32_16x16x32_bf16 v[52:55], v[170:173], v[80:83], v[52:55]
	v_mfma_f32_16x16x32_bf16 v[48:51], v[170:173], v[88:91], v[48:51]
	ds_read_b64_tr_b16 v[162:163], v139 offset:18016
	ds_read_b64_tr_b16 v[164:165], v139 offset:20320
	v_mfma_f32_16x16x32_bf16 v[60:63], v[198:201], v[80:83], v[60:63]
	v_mfma_f32_16x16x32_bf16 v[56:59], v[198:201], v[88:91], v[56:59]
	s_waitcnt lgkmcnt(12)
	v_mfma_f32_16x16x32_bf16 v[68:71], v[210:213], v[80:83], v[68:71]
	v_mfma_f32_16x16x32_bf16 v[64:67], v[210:213], v[88:91], v[64:67]
	s_waitcnt lgkmcnt(10)
	v_mfma_f32_16x16x32_bf16 v[44:47], v[214:217], v[80:83], v[44:47]
	v_mfma_f32_16x16x32_bf16 v[40:43], v[214:217], v[88:91], v[40:43]
	s_waitcnt lgkmcnt(8)
	v_mfma_f32_16x16x32_bf16 v[36:39], v[218:221], v[80:83], v[36:39]
	v_mfma_f32_16x16x32_bf16 v[32:35], v[218:221], v[88:91], v[32:35]
	v_mfma_f32_16x16x32_bf16 v[60:63], v[198:201], v[96:99], v[60:63]
	v_mfma_f32_16x16x32_bf16 v[56:59], v[198:201], v[104:107], v[56:59]
	s_waitcnt lgkmcnt(6)
	v_mfma_f32_16x16x32_bf16 v[52:55], v[240:243], v[96:99], v[52:55]
	v_mfma_f32_16x16x32_bf16 v[48:51], v[240:243], v[104:107], v[48:51]
	s_waitcnt lgkmcnt(4)
	v_mfma_f32_16x16x32_bf16 v[68:71], v[244:247], v[96:99], v[68:71]
	v_mfma_f32_16x16x32_bf16 v[64:67], v[244:247], v[104:107], v[64:67]
	s_waitcnt lgkmcnt(2)
	v_mfma_f32_16x16x32_bf16 v[44:47], v[158:161], v[96:99], v[44:47]
	v_mfma_f32_16x16x32_bf16 v[40:43], v[158:161], v[104:107], v[40:43]
	s_waitcnt lgkmcnt(0)
	v_mfma_f32_16x16x32_bf16 v[36:39], v[162:165], v[96:99], v[36:39]
	v_mfma_f32_16x16x32_bf16 v[32:35], v[162:165], v[104:107], v[32:35]
	s_branch .LBB0_392

; #define LAS __attribute__((address_space(3)))
; __device__ __forceinline__ f32x4 mfma16(bf16x8 a, bf16x8 b, f32x4 c) { return __builtin_amdgcn_mfma_f32_16x16x32_bf16(a, b, c, 0, 0, 0); }
; __device__ __forceinline__ void attn_unit(LAS unsigned char* lds, const bf16_t* Q, const bf16_t* KV, const bf16_t* KR, bf16_t* MIX, size_t qrow0, size_t krow0, int ntiles, int h, const int tid) {
;     ...
;     if (more) { const bf16_t* g2 = gk + (size_t)(t + 1) * 64 * 1024; rk = *(const u32x4*)g2; rv = *(const u32x4*)(g2 + 64); if (tid < 256) rr = *(const u32x4*)(gr + (size_t)(t + 1) * 64 * 32); }
;     const LAS bf16_t* Ks = (const LAS bf16_t*)buf; const LAS bf16_t* Vs = (const LAS bf16_t*)(buf + 64 * AT_KSTR * 2);
;     f32x4 s[4][2];
; #pragma unroll
;     for (int kb = 0; kb < 4; ++kb) {
;       bf16x8 kf[3];
; #pragma unroll
;       for (int ks = 0; ks < 3; ++ks) kf[ks] = *(const LAS bf16x8*)(Ks + (kb * 16 + c16) * AT_KSTR + ks * 32 + quad * 8);
; #pragma unroll
;       for (int qb = 0; qb < 2; ++qb) { const float nm = -mref[qb]; f32x4 a = (f32x4){nm, nm, nm, nm};
; #pragma unroll
;         for (int ks = 0; ks < 3; ++ks) a = mfma16(kf[ks], qf[qb][ks], a);
;         s[kb][qb] = a; }
;     }
; #pragma unroll
;     for (int qb = 0; qb < 2; ++qb) {
;       float mx = -1e30f;
; #pragma unroll
;       for (int kb = 0; kb < 4; ++kb) mx = fmaxf(fmaxf(fmaxf(s[kb][qb][0], s[kb][qb][1]), fmaxf(s[kb][qb][2], s[kb][qb][3])), mx);
;       mx = fmaxf(mx, __shfl_xor(mx, 16)); mx = fmaxf(mx, __shfl_xor(mx, 32));
;       if (t == 0 || __any(mx > 8.f)) {
.LBB0_386:
	s_or_b64 exec, exec, s[0:1]
	v_add3_u32 v0, s12, v124, v146
	ds_read_b128 v[158:161], v0
	ds_read_b128 v[162:165], v0 offset:64
	ds_read_b128 v[166:169], v0 offset:128
	ds_read_b128 v[170:173], v0 offset:3328
	ds_read_b128 v[210:213], v0 offset:3392
	ds_read_b128 v[214:217], v0 offset:3456
	ds_read_b128 v[218:221], v0 offset:6656
	ds_read_b128 v[240:243], v0 offset:6720
	ds_read_b128 v[244:247], v0 offset:6784
	v_add3_u32 v139, s12, v176, v155
	s_waitcnt lgkmcnt(8)
	v_mfma_f32_16x16x32_bf16 v[80:83], v[158:161], v[4:7], v[202:205]
	v_mfma_f32_16x16x32_bf16 v[88:91], v[158:161], v[16:19], v[206:209]
	s_waitcnt lgkmcnt(7)
	v_mfma_f32_16x16x32_bf16 v[80:83], v[162:165], v[8:11], v[80:83]
	v_mfma_f32_16x16x32_bf16 v[88:91], v[162:165], v[20:23], v[88:91]
	s_waitcnt lgkmcnt(6)
	v_mfma_f32_16x16x32_bf16 v[80:83], v[166:169], v[12:15], v[80:83]
	v_mfma_f32_16x16x32_bf16 v[88:91], v[166:169], v[24:27], v[88:91]
	ds_read_b128 v[158:161], v0 offset:9984
	ds_read_b128 v[162:165], v0 offset:10048
	ds_read_b128 v[166:169], v0 offset:10112
	s_waitcnt lgkmcnt(8)
	v_mfma_f32_16x16x32_bf16 v[84:87], v[170:173], v[4:7], v[202:205]
	v_mfma_f32_16x16x32_bf16 v[92:95], v[170:173], v[16:19], v[206:209]
	s_waitcnt lgkmcnt(7)
	v_mfma_f32_16x16x32_bf16 v[84:87], v[210:213], v[8:11], v[84:87]
	v_mfma_f32_16x16x32_bf16 v[92:95], v[210:213], v[20:23], v[92:95]
	s_waitcnt lgkmcnt(6)
	v_mfma_f32_16x16x32_bf16 v[84:87], v[214:217], v[12:15], v[84:87]
	v_mfma_f32_16x16x32_bf16 v[92:95], v[214:217], v[24:27], v[92:95]
	ds_read_b64_tr_b16 v[170:171], v139 offset:13312
	ds_read_b64_tr_b16 v[172:173], v139 offset:15616
	ds_read_b64_tr_b16 v[210:211], v139 offset:13344
	ds_read_b64_tr_b16 v[212:213], v139 offset:15648
	ds_read_b64_tr_b16 v[214:215], v139 offset:13376
	ds_read_b64_tr_b16 v[216:217], v139 offset:15680
	s_waitcnt lgkmcnt(11)
	v_mfma_f32_16x16x32_bf16 v[96:99], v[218:221], v[4:7], v[202:205]
	v_mfma_f32_16x16x32_bf16 v[104:107], v[218:221], v[16:19], v[206:209]
	v_max3_f32 v174, v80, v81, v82
	s_waitcnt lgkmcnt(10)
	v_mfma_f32_16x16x32_bf16 v[96:99], v[240:243], v[8:11], v[96:99]
	v_mfma_f32_16x16x32_bf16 v[104:107], v[240:243], v[20:23], v[104:107]
	v_max3_f32 v175, v88, v89, v90
	s_waitcnt lgkmcnt(9)
	v_mfma_f32_16x16x32_bf16 v[96:99], v[244:247], v[12:15], v[96:99]
	v_mfma_f32_16x16x32_bf16 v[104:107], v[244:247], v[24:27], v[104:107]
	ds_read_b64_tr_b16 v[218:219], v139 offset:13408
	ds_read_b64_tr_b16 v[220:221], v139 offset:15712
	s_waitcnt lgkmcnt(10)
	v_mfma_f32_16x16x32_bf16 v[100:103], v[158:161], v[4:7], v[202:205]
	v_mfma_f32_16x16x32_bf16 v[108:111], v[158:161], v[16:19], v[206:209]
	v_max3_f32 v174, v174, v83, v84
	s_waitcnt lgkmcnt(9)
	v_mfma_f32_16x16x32_bf16 v[100:103], v[162:165], v[8:11], v[100:103]
	v_max3_f32 v174, v174, v85, v86
	v_mfma_f32_16x16x32_bf16 v[108:111], v[162:165], v[20:23], v[108:111]
	s_waitcnt lgkmcnt(8)
	v_mfma_f32_16x16x32_bf16 v[100:103], v[166:169], v[12:15], v[100:103]
	v_max3_f32 v175, v175, v91, v92
	v_mfma_f32_16x16x32_bf16 v[108:111], v[166:169], v[24:27], v[108:111]
	v_max3_f32 v175, v175, v93, v94
	v_max3_f32 v174, v174, v87, v96
	v_max3_f32 v174, v174, v97, v98
	v_max3_f32 v175, v175, v95, v104
	v_max3_f32 v175, v175, v105, v106
	ds_read_b64_tr_b16 v[240:241], v139 offset:17920
	ds_read_b64_tr_b16 v[242:243], v139 offset:20224
	ds_read_b64_tr_b16 v[244:245], v139 offset:17952
	ds_read_b64_tr_b16 v[246:247], v139 offset:20256
	ds_read_b64_tr_b16 v[158:159], v139 offset:17984
	ds_read_b64_tr_b16 v[160:161], v139 offset:20288
	v_max3_f32 v174, v174, v99, v100
	v_max3_f32 v175, v175, v107, v108
	v_max3_f32 v174, v174, v101, v102
	v_max3_f32 v175, v175, v109, v110
	v_max_f32_e32 v174, v174, v103
	v_max_f32_e32 v175, v175, v111
	v_max_f32_e32 v0, v174, v175
	v_cmp_lt_f32_e32 vcc, 0x41000000, v0
	s_cbranch_vccnz .Lat_rareA
; #define LAS __attribute__((address_space(3)))
; __device__ __forceinline__ unsigned cvtpk(float lo, float hi) { f32x2_t v = {lo, hi}; bf16x2_t b = __builtin_convertvector(v, bf16x2_t); return __builtin_bit_cast(unsigned, b); }
; __device__ __forceinline__ f32x4 mfma16(bf16x8 a, bf16x8 b, f32x4 c) { return __builtin_amdgcn_mfma_f32_16x16x32_bf16(a, b, c, 0, 0, 0); }
; __device__ __forceinline__ u32x2 tr_rd(const LAS bf16_t* p) { return __builtin_bit_cast(u32x2, __builtin_amdgcn_ds_read_tr16_b64_v4i16((LAS v4i16_t*)p)); }
; __device__ __forceinline__ void attn_unit(LAS unsigned char* lds, const bf16_t* Q, const bf16_t* KV, const bf16_t* KR, bf16_t* MIX, size_t qrow0, size_t krow0, int ntiles, int h, const int tid) {
;     ...
;         for (int r = 0; r < 4; ++r) s[kb][qb][r] = __builtin_amdgcn_exp2f(s[kb][qb][r]);
;     }
; #pragma unroll
;     for (int s2 = 0; s2 < 2; ++s2) {
;       bf16x8 pf[2];
; #pragma unroll
;       for (int qb = 0; qb < 2; ++qb) { u32x4 w; w.x = cvtpk(s[2 * s2][qb][0], s[2 * s2][qb][1]); w.y = cvtpk(s[2 * s2][qb][2], s[2 * s2][qb][3]);
;         w.z = cvtpk(s[2 * s2 + 1][qb][0], s[2 * s2 + 1][qb][1]); w.w = cvtpk(s[2 * s2 + 1][qb][2], s[2 * s2 + 1][qb][3]); pf[qb] = __builtin_bit_cast(bf16x8, w);
;         lacc[qb] = mfma16(ones, pf[qb], lacc[qb]); }
;       const LAS bf16_t* vb = Vs + (32 * s2 + 4 * quad + tq) * AT_VSTR + 4 * tp;
; #pragma unroll
;       for (int eb = 0; eb < 4; ++eb) {
;         const u32x2 lo = tr_rd(vb + 16 * eb), hi = tr_rd(vb + 16 * AT_VSTR + 16 * eb);
;         const u32x4 vv = (u32x4){lo.x, lo.y, hi.x, hi.y}; const bf16x8 vf = __builtin_bit_cast(bf16x8, vv);
; #pragma unroll
;         for (int qb = 0; qb < 2; ++qb) o[qb][eb] = mfma16(vf, pf[qb], o[qb][eb]);
;       }
;     }
;     if (more) attn_stage(lds + ((t + 1) & 1) * AT_BUF, tid, rk, rv, rr);
;     __syncthreads();
.Lat_backA:
	v_exp_f32_e32 v80, v80
	v_exp_f32_e32 v81, v81
	v_exp_f32_e32 v82, v82
	v_exp_f32_e32 v83, v83
	v_exp_f32_e32 v84, v84
	v_exp_f32_e32 v85, v85
	v_exp_f32_e32 v86, v86
	v_exp_f32_e32 v87, v87
	v_cvt_pk_bf16_f32 v80, v80, v81
	v_cvt_pk_bf16_f32 v81, v82, v83
	v_cvt_pk_bf16_f32 v82, v84, v85
	v_cvt_pk_bf16_f32 v83, v86, v87
	v_exp_f32_e32 v88, v88
	v_exp_f32_e32 v89, v89
	v_exp_f32_e32 v90, v90
	v_exp_f32_e32 v91, v91
	v_exp_f32_e32 v92, v92
	v_exp_f32_e32 v93, v93
	v_exp_f32_e32 v94, v94
	v_exp_f32_e32 v95, v95
	v_cvt_pk_bf16_f32 v88, v88, v89
	v_cvt_pk_bf16_f32 v89, v90, v91
	v_cvt_pk_bf16_f32 v90, v92, v93
	v_cvt_pk_bf16_f32 v91, v94, v95
	s_waitcnt lgkmcnt(12)
	v_mfma_f32_16x16x32_bf16 v[52:55], v[170:173], v[80:83], v[52:55]
	v_exp_f32_e32 v96, v96
	v_exp_f32_e32 v97, v97
	v_mfma_f32_16x16x32_bf16 v[48:51], v[170:173], v[88:91], v[48:51]
	v_exp_f32_e32 v98, v98
	v_exp_f32_e32 v99, v99
	v_mfma_f32_16x16x32_bf16 v[60:63], v[198:201], v[80:83], v[60:63]
	v_exp_f32_e32 v100, v100
	v_exp_f32_e32 v101, v101
	v_mfma_f32_16x16x32_bf16 v[56:59], v[198:201], v[88:91], v[56:59]
	v_exp_f32_e32 v102, v102
	v_exp_f32_e32 v103, v103
	s_waitcnt lgkmcnt(10)
	v_mfma_f32_16x16x32_bf16 v[68:71], v[210:213], v[80:83], v[68:71]
	v_exp_f32_e32 v104, v104
	v_exp_f32_e32 v105, v105
	v_mfma_f32_16x16x32_bf16 v[64:67], v[210:213], v[88:91], v[64:67]
	v_exp_f32_e32 v106, v106
	v_exp_f32_e32 v107, v107
	s_waitcnt lgkmcnt(8)
	v_mfma_f32_16x16x32_bf16 v[44:47], v[214:217], v[80:83], v[44:47]
	v_exp_f32_e32 v108, v108
	v_exp_f32_e32 v109, v109
	v_mfma_f32_16x16x32_bf16 v[40:43], v[214:217], v[88:91], v[40:43]
	v_exp_f32_e32 v110, v110
	v_exp_f32_e32 v111, v111
	s_waitcnt lgkmcnt(6)
	v_mfma_f32_16x16x32_bf16 v[36:39], v[218:221], v[80:83], v[36:39]
	v_cvt_pk_bf16_f32 v96, v96, v97
	v_cvt_pk_bf16_f32 v97, v98, v99
	v_mfma_f32_16x16x32_bf16 v[32:35], v[218:221], v[88:91], v[32:35]
	v_cvt_pk_bf16_f32 v98, v100, v101
	v_cvt_pk_bf16_f32 v99, v102, v103
	ds_read_b64_tr_b16 v[162:163], v139 offset:18016
	ds_read_b64_tr_b16 v[164:165], v139 offset:20320
	v_cvt_pk_bf16_f32 v104, v104, v105
	v_cvt_pk_bf16_f32 v105, v106, v107
	v_cvt_pk_bf16_f32 v106, v108, v109
	v_cvt_pk_bf16_f32 v107, v110, v111
	v_mfma_f32_16x16x32_bf16 v[60:63], v[198:201], v[96:99], v[60:63]
	v_add3_u32 v0, s13, v148, v138
	v_add3_u32 v177, s13, v127, v138
	v_mfma_f32_16x16x32_bf16 v[56:59], v[198:201], v[104:107], v[56:59]
	s_waitcnt lgkmcnt(6)
	v_mfma_f32_16x16x32_bf16 v[52:55], v[240:243], v[96:99], v[52:55]
	v_mfma_f32_16x16x32_bf16 v[48:51], v[240:243], v[104:107], v[48:51]
	s_waitcnt lgkmcnt(4)
	v_mfma_f32_16x16x32_bf16 v[68:71], v[244:247], v[96:99], v[68:71]
	v_mfma_f32_16x16x32_bf16 v[64:67], v[244:247], v[104:107], v[64:67]
	s_waitcnt lgkmcnt(2)
	v_mfma_f32_16x16x32_bf16 v[44:47], v[158:161], v[96:99], v[44:47]
	v_mfma_f32_16x16x32_bf16 v[40:43], v[158:161], v[104:107], v[40:43]
	s_waitcnt lgkmcnt(0)
	v_mfma_f32_16x16x32_bf16 v[36:39], v[162:165], v[96:99], v[36:39]
	v_mfma_f32_16x16x32_bf16 v[32:35], v[162:165], v[104:107], v[32:35]
	s_waitcnt vmcnt(0)
	ds_write_b128 v0, v[76:79]
	ds_write_b128 v177, v[72:75] offset:13312
	s_and_saveexec_b64 s[0:1], s[42:43]
	s_cbranch_execz .LBB0_383
	v_add3_u32 v0, s13, v149, v126
	ds_write_b128 v0, v[28:31] offset:128
.LBB0_383:
	s_or_b64 exec, exec, s[0:1]
	s_mov_b64 s[0:1], 0x1000
	s_add_i32 s4, s4, 1
	v_lshl_add_u64 v[140:141], v[140:141], 0, s[0:1]
	s_mov_b64 s[0:1], 0x20000
	v_lshl_add_u64 v[142:143], v[142:143], 0, s[0:1]
	s_mov_b32 s14, s12
	s_mov_b32 s12, s13
	s_add_i32 s13, s13, 0x5800
	s_cmp_eq_u32 s13, 0x10800
	s_cselect_b32 s13, 0, s13
	s_cmpk_lg_i32 s4, 0x84
	s_waitcnt lgkmcnt(0)
	s_cbranch_scc1 .Lat_A_head
	s_barrier
